# attention loop: static s_setprio 1 for the later-dispatched co-resident block (blockIdx>=256)
# speedup vs baseline: 1.0358x; 1.0076x over previous
; __device__ __forceinline__ void attn_item(const P& p, int layer, int item, char* lds) {
;   const int tid = ltid(), wid = tid >> 6, lane = tid & 63, r32 = lane & 31, hi = lane >> 5;
;   const int qb = item & 63, h = (item >> 6) & 3, b = item >> 8;
;   const u16* z = (const u16*)(p.ws + OFF_Z);
;   const long tokb = (long)b * SEQ, tokq = tokb + qb * 128;
;   constexpr int STG = 2 * ATT_KB + ATT_VB;
;   float* wsf = (float*)(lds + 2 * STG) + wid * 64;
;   float* li_l = wsf; float* al_l = wsf + 32;
;   const int vb0 = (int)(uintptr_t)(lds + 2 * ATT_KB) + v_rd_base(lane);
;   const int koff = r32 * 128, ksw = (r32 >> 1) & 7;
;   const unsigned k_src = (tid >> 3) * ZC + (((tid & 7) ^ ((tid >> 4) & 7)) << 3);
;   const int v_kl = (tid & 31) >> 2;
;   const unsigned v_src = (v_kl | ((tid >> 7) << 3)) * ZC + ((tid >> 5) & 3) * 32 + (tid & 3) * 8;
;   char* lw = lds + tid * 16;
;   const float lam = ((const float*)(p.ws + OFF_LAM))[layer];
;   const u16* Kg = z + tokb * ZC + C_DAK + h * 128; const u16* Vg = z + tokb * ZC + C_DAV + h * 128;
;   bf16x8 q1[4], q2[2];
;   char* Qp = lds + 2 * STG + 1024 + tid * 16;
; #pragma unroll
;   for (int d0 = 0; d0 < 4; ++d0) q1[d0] = *(const bf16x8*)(z + (tokq + wid * 32 + r32) * ZC + h * 128 + d0 * 16 + hi * 8);
; #pragma unroll
;   for (int d0 = 0; d0 < 2; ++d0) q2[d0] = *(const bf16x8*)(z + (tokq + wid * 32 + r32) * ZC + h * 128 + 64 + d0 * 16 + hi * 8);
;   __syncthreads();
;   float qs1 = 0.f, qs2 = 0.f;
; #pragma unroll
;   for (int d0 = 0; d0 < 4; ++d0) qs1 += sumsq8(q1[d0]);
; #pragma unroll
;   for (int d0 = 0; d0 < 2; ++d0) qs2 += sumsq8(q2[d0]);
; #pragma unroll
;   for (int d0 = 2; d0 < 4; ++d0) { const bf16x8 t = *(const bf16x8*)(z + (tokq + wid * 32 + r32) * ZC + h * 128 + 64 + d0 * 16 + hi * 8);
;     qs2 += sumsq8(t); *(bf16x8*)(Qp + (d0 - 2) * 4096) = t; }
;   { auto rr = __builtin_amdgcn_permlane32_swap(__float_as_uint(qs1), __float_as_uint(qs1), false, false); qs1 = __uint_as_float(rr[0]) + __uint_as_float(rr[1]); }
;   { auto rr = __builtin_amdgcn_permlane32_swap(__float_as_uint(qs2), __float_as_uint(qs2), false, false); qs2 = __uint_as_float(rr[0]) + __uint_as_float(rr[1]); }
;   float mC1, mC2;
;   { const float* kmx = (const float*)(p.ws + OFF_KMX) + (size_t)((b * 4 + h) * 2) * 128;
;     float k1 = fmaxf(kmx[lane], kmx[64 + lane]), k2 = fmaxf(kmx[128 + lane], kmx[192 + lane]);
.LBB0_271:
	s_lshl_b32 s3, s83, 3
	s_and_b32 s3, s3, 0xfffffe00
	v_readlane_b32 s6, v253, 38
	s_or_b32 s8, s3, s6
	v_mov_b32_e32 v214, v229
	s_ashr_i32 s6, s8, 8
	s_ashr_i32 s7, s6, 31
	s_lshl_b32 s3, s83, 7
	s_waitcnt vmcnt(7)
	v_ashrrev_i32_e32 v0, 1, v214
	s_lshl_b64 s[70:71], s[6:7], 13
	s_and_b32 s3, s3, 0x1f80
	v_and_b32_e32 v202, 0xffffffe0, v0
	s_or_b32 s70, s70, s3
	v_ashrrev_i32_e32 v203, 31, v202
	v_and_b32_e32 v226, 31, v214
	v_lshl_add_u64 v[0:1], s[70:71], 0, v[202:203]
	v_or_b32_e32 v0, v0, v226
	v_mov_b64_e32 v[2:3], s[58:59]
	v_bfe_u32 v227, v214, 5, 1
	v_mad_u64_u32 v[2:3], s[18:19], v0, s9, v[2:3]
	v_mad_i32_i24 v3, v1, s9, v3
	v_lshlrev_b32_e32 v200, 4, v227
	v_lshl_add_u64 v[0:1], v[2:3], 0, v[200:201]
	global_load_dwordx4 v[180:183], v[0:1], off
	global_load_dwordx4 v[176:179], v[0:1], off offset:32
	global_load_dwordx4 v[172:175], v[0:1], off offset:64
	global_load_dword v225, v201, s[42:43]
	global_load_dwordx4 v[168:171], v[0:1], off offset:96
	global_load_dwordx4 v[164:167], v[0:1], off offset:128
	global_load_dwordx4 v[160:163], v[0:1], off offset:160
	v_lshlrev_b32_e32 v2, 1, v214
	s_waitcnt vmcnt(13)
	v_lshrrev_b32_e32 v4, 4, v214
	v_lshrrev_b32_e32 v3, 3, v214
	v_bfe_u32 v6, v214, 2, 3
	s_waitcnt vmcnt(12)
	v_ashrrev_i32_e32 v8, 4, v214
	v_and_b32_e32 v11, 32, v2
	v_xor_b32_e32 v2, v4, v214
	s_mov_b32 s3, 0xfffff8
	s_movk_i32 s33, 0xb00
	v_and_or_b32 v4, v8, s3, v6
	v_mul_lo_u32 v3, v3, s33
	s_waitcnt vmcnt(11)
	v_lshlrev_b32_e32 v14, 3, v2
	v_mul_u32_u24_e32 v2, 0xb00, v4
	v_and_or_b32 v4, v14, 56, v3
	s_barrier
	global_load_dwordx4 v[14:17], v[0:1], off offset:192
	s_mul_i32 s7, s6, 0x2c00000
	s_mul_hi_i32 s3, s6, 0x2c00000
	s_add_u32 s76, s58, s7
	s_addc_u32 s77, s59, s3
	s_ashr_i32 s6, s8, 5
	v_readlane_b32 s8, v253, 40
	s_or_b32 s18, s6, s8
	s_ashr_i32 s19, s18, 31
	s_lshl_b64 s[18:19], s[18:19], 9
	v_and_b32_e32 v228, 63, v214
	s_add_u32 s18, s73, s18
	s_addc_u32 s19, s80, s19
	v_lshlrev_b32_e32 v5, 4, v214
	v_and_b32_e32 v13, 0xc0, v5
	v_add_u32_e32 v232, 0, v5
	v_add_u32_e32 v230, 0x10400, v232
	s_mov_b32 s52, 0xf800000
	v_readfirstlane_b32 s8, v232
	s_mov_b32 m0, s8
	v_lshlrev_b32_e32 v10, 3, v214
	v_and_b32_e32 v7, 0x60, v214
	v_and_b32_e32 v12, 24, v10
	v_or3_b32 v2, v2, v7, v12
	s_cmp_lg_u32 0, -1
	v_lshrrev_b32_e32 v9, 1, v214
	s_mov_b32 s6, 0
	v_lshl_add_u32 v236, v226, 7, 0
	s_movk_i32 s11, 0xb00
	s_waitcnt vmcnt(7)
	v_and_b32_e32 v18, 0xffff0000, v180
	s_waitcnt vmcnt(6)
	v_and_b32_e32 v26, 0xffff0000, v176
	v_lshlrev_b32_e32 v3, 16, v180
	v_lshlrev_b32_e32 v25, 16, v176
	v_mul_f32_e32 v18, v18, v18
	v_mul_f32_e32 v26, v26, v26
	v_lshlrev_b32_e32 v19, 16, v181
	v_lshlrev_b32_e32 v27, 16, v177
	v_fmac_f32_e32 v18, v3, v3
	v_fmac_f32_e32 v26, v25, v25
	v_and_b32_e32 v20, 0xffff0000, v181
	v_and_b32_e32 v28, 0xffff0000, v177
	v_fmac_f32_e32 v18, v19, v19
	v_fmac_f32_e32 v26, v27, v27
	v_lshlrev_b32_e32 v21, 16, v182
	v_lshlrev_b32_e32 v29, 16, v178
	s_waitcnt vmcnt(5)
	v_and_b32_e32 v34, 0xffff0000, v172
	v_fmac_f32_e32 v18, v20, v20
	v_fmac_f32_e32 v26, v28, v28
	v_and_b32_e32 v22, 0xffff0000, v182
	v_and_b32_e32 v30, 0xffff0000, v178
	v_lshlrev_b32_e32 v33, 16, v172
	v_mul_f32_e32 v34, v34, v34
	v_fmac_f32_e32 v18, v21, v21
	v_fmac_f32_e32 v26, v29, v29
	v_lshlrev_b32_e32 v23, 16, v183
	v_lshlrev_b32_e32 v31, 16, v179
	v_lshlrev_b32_e32 v35, 16, v173
	v_fmac_f32_e32 v34, v33, v33
	v_fmac_f32_e32 v18, v22, v22
	v_fmac_f32_e32 v26, v30, v30
	v_and_b32_e32 v24, 0xffff0000, v183
	v_and_b32_e32 v32, 0xffff0000, v179
	v_and_b32_e32 v36, 0xffff0000, v173
	v_fmac_f32_e32 v34, v35, v35
	v_fmac_f32_e32 v18, v23, v23
	v_fmac_f32_e32 v26, v31, v31
	v_lshlrev_b32_e32 v37, 16, v174
	v_fmac_f32_e32 v34, v36, v36
	v_fmac_f32_e32 v18, v24, v24
	v_fmac_f32_e32 v26, v32, v32
	v_fmac_f32_e32 v34, v37, v37
	v_add_f32_e32 v3, v18, v26
	v_and_b32_e32 v18, 0xffff0000, v174
	v_fmac_f32_e32 v34, v18, v18
	v_lshlrev_b32_e32 v18, 16, v175
	v_fmac_f32_e32 v34, v18, v18
	v_and_b32_e32 v18, 0xffff0000, v175
	v_fmac_f32_e32 v34, v18, v18
	s_waitcnt vmcnt(3)
	v_and_b32_e32 v23, 0xffff0000, v168
	global_load_dwordx4 v[18:21], v[0:1], off offset:224
	v_lshlrev_b32_e32 v1, 2, v228
	v_mul_f32_e32 v0, v23, v23
	global_load_dword v23, v1, s[18:19] offset:256
	global_load_dword v24, v1, s[18:19] offset:512
	global_load_dword v25, v1, s[18:19] offset:768
	s_nop 0
	global_load_dword v1, v1, s[18:19]
	v_lshlrev_b32_e32 v22, 16, v168
	v_fmac_f32_e32 v0, v22, v22
	v_lshlrev_b32_e32 v22, 16, v169
	v_fmac_f32_e32 v0, v22, v22
	v_and_b32_e32 v22, 0xffff0000, v169
	v_fmac_f32_e32 v0, v22, v22
	v_lshlrev_b32_e32 v22, 16, v170
	v_fmac_f32_e32 v0, v22, v22
	v_and_b32_e32 v22, 0xffff0000, v170
	v_fmac_f32_e32 v0, v22, v22
	v_lshlrev_b32_e32 v22, 16, v171
	v_fmac_f32_e32 v0, v22, v22
	v_and_b32_e32 v22, 0xffff0000, v171
	v_add_f32_e32 v3, v3, v34
	v_fmac_f32_e32 v0, v22, v22
	s_waitcnt vmcnt(7)
	v_and_b32_e32 v5, 0xffff0000, v164
	v_add_f32_e32 v0, v3, v0
	v_lshlrev_b32_e32 v3, 16, v164
	v_mul_f32_e32 v5, v5, v5
	v_fmac_f32_e32 v5, v3, v3
	v_lshlrev_b32_e32 v3, 16, v165
	v_fmac_f32_e32 v5, v3, v3
	v_and_b32_e32 v3, 0xffff0000, v165
	v_fmac_f32_e32 v5, v3, v3
	v_lshlrev_b32_e32 v3, 16, v166
	v_fmac_f32_e32 v5, v3, v3
	v_and_b32_e32 v3, 0xffff0000, v166
	v_fmac_f32_e32 v5, v3, v3
	v_lshlrev_b32_e32 v3, 16, v167
	v_fmac_f32_e32 v5, v3, v3
	v_and_b32_e32 v3, 0xffff0000, v167
	s_waitcnt vmcnt(6)
; __device__ __forceinline__ void attn_item(const P& p, int layer, int item, char* lds) {
;     ...
;   float qs1 = 0.f, qs2 = 0.f;
; #pragma unroll
;   for (int d0 = 0; d0 < 4; ++d0) qs1 += sumsq8(q1[d0]);
; #pragma unroll
;   for (int d0 = 0; d0 < 2; ++d0) qs2 += sumsq8(q2[d0]);
; #pragma unroll
;   for (int d0 = 2; d0 < 4; ++d0) { const bf16x8 t = *(const bf16x8*)(z + (tokq + wid * 32 + r32) * ZC + h * 128 + 64 + d0 * 16 + hi * 8);
;     qs2 += sumsq8(t); *(bf16x8*)(Qp + (d0 - 2) * 4096) = t; }
;   { auto rr = __builtin_amdgcn_permlane32_swap(__float_as_uint(qs1), __float_as_uint(qs1), false, false); qs1 = __uint_as_float(rr[0]) + __uint_as_float(rr[1]); }
;   { auto rr = __builtin_amdgcn_permlane32_swap(__float_as_uint(qs2), __float_as_uint(qs2), false, false); qs2 = __uint_as_float(rr[0]) + __uint_as_float(rr[1]); }
;   float mC1, mC2;
;   { const float* kmx = (const float*)(p.ws + OFF_KMX) + (size_t)((b * 4 + h) * 2) * 128;
;     float k1 = fmaxf(kmx[lane], kmx[64 + lane]), k2 = fmaxf(kmx[128 + lane], kmx[192 + lane]);
; #pragma unroll
;     for (int o = 32; o >= 1; o >>= 1) { k1 = fmaxf(k1, __shfl_xor(k1, o)); k2 = fmaxf(k2, __shfl_xor(k2, o)); }
;     mC1 = sqrtf(qs1 * k1) * 1.4426950408889634f; mC2 = sqrtf(qs2 * k2) * 1.4426950408889634f; }
;   float l1 = 0.f, l2 = 0.f;
;   f32x16 o1[4], o2[4];
; #pragma unroll
;   for (int d = 0; d < 4; ++d) { o1[d] = f32x16{}; o2[d] = f32x16{}; }
;     ...
;   __syncthreads();
;   ISSUE_T(0, 0);
	v_and_b32_e32 v22, 0xffff0000, v160
	v_fmac_f32_e32 v5, v3, v3
	v_lshlrev_b32_e32 v3, 16, v160
	v_mul_f32_e32 v22, v22, v22
	v_fmac_f32_e32 v22, v3, v3
	v_lshlrev_b32_e32 v3, 16, v161
	v_fmac_f32_e32 v22, v3, v3
	v_and_b32_e32 v3, 0xffff0000, v161
	v_fmac_f32_e32 v22, v3, v3
	v_lshlrev_b32_e32 v3, 16, v162
	v_fmac_f32_e32 v22, v3, v3
	v_and_b32_e32 v3, 0xffff0000, v162
	v_fmac_f32_e32 v22, v3, v3
	v_lshlrev_b32_e32 v3, 16, v163
	v_fmac_f32_e32 v22, v3, v3
	v_and_b32_e32 v3, 0xffff0000, v163
	v_fmac_f32_e32 v22, v3, v3
	v_add_f32_e32 v3, v5, v22
	s_waitcnt vmcnt(5)
	v_and_b32_e32 v22, 0xffff0000, v14
	v_lshlrev_b32_e32 v5, 16, v14
	v_mul_f32_e32 v22, v22, v22
	v_fmac_f32_e32 v22, v5, v5
	v_lshlrev_b32_e32 v5, 16, v15
	v_fmac_f32_e32 v22, v5, v5
	v_and_b32_e32 v5, 0xffff0000, v15
	v_fmac_f32_e32 v22, v5, v5
	v_lshlrev_b32_e32 v5, 16, v16
	v_fmac_f32_e32 v22, v5, v5
	v_and_b32_e32 v5, 0xffff0000, v16
	v_fmac_f32_e32 v22, v5, v5
	v_lshlrev_b32_e32 v5, 16, v17
	v_fmac_f32_e32 v22, v5, v5
	v_and_b32_e32 v5, 0xffff0000, v17
	v_fmac_f32_e32 v22, v5, v5
	ds_write_b128 v230, v[14:17]
	v_and_b32_e32 v17, 64, v250
	v_add_f32_e32 v3, v3, v22
	v_add_u32_e32 v17, 64, v17
	v_xor_b32_e32 v22, 32, v250
	v_cmp_lt_i32_e32 vcc, v22, v17
	s_mov_b64 s[18:19], 0x2c400
	s_waitcnt vmcnt(3)
	v_max_f32_e32 v15, v23, v23
	v_cndmask_b32_e32 v22, v250, v22, vcc
	v_lshlrev_b32_e32 v22, 2, v22
	s_waitcnt vmcnt(0)
	v_max_f32_e32 v1, v1, v1
	v_max_f32_e32 v1, v1, v15
	ds_bpermute_b32 v23, v22, v1
	v_max_f32_e32 v15, v25, v25
	v_max_f32_e32 v16, v24, v24
	v_max_f32_e32 v15, v16, v15
	ds_bpermute_b32 v16, v22, v15
	s_waitcnt lgkmcnt(1)
	v_max_f32_e32 v22, v23, v23
	v_max_f32_e32 v1, v1, v22
	v_xor_b32_e32 v22, 16, v250
	v_cmp_lt_i32_e32 vcc, v22, v17
	s_waitcnt lgkmcnt(0)
	v_max_f32_e32 v16, v16, v16
	v_max_f32_e32 v15, v15, v16
	v_cndmask_b32_e32 v22, v250, v22, vcc
	v_lshlrev_b32_e32 v203, 2, v22
	ds_bpermute_b32 v22, v203, v1
	v_and_b32_e32 v14, 0xffff0000, v18
	ds_bpermute_b32 v16, v203, v15
	v_lshlrev_b32_e32 v5, 16, v18
	v_mul_f32_e32 v14, v14, v14
	s_waitcnt lgkmcnt(1)
	v_max_f32_e32 v22, v22, v22
	v_fmac_f32_e32 v14, v5, v5
	v_lshlrev_b32_e32 v5, 16, v19
	v_max_f32_e32 v1, v1, v22
	v_xor_b32_e32 v22, 8, v250
	v_fmac_f32_e32 v14, v5, v5
	v_and_b32_e32 v5, 0xffff0000, v19
	v_cmp_lt_i32_e32 vcc, v22, v17
	v_fmac_f32_e32 v14, v5, v5
	v_lshlrev_b32_e32 v5, 16, v20
	v_cndmask_b32_e32 v22, v250, v22, vcc
	v_fmac_f32_e32 v14, v5, v5
	v_and_b32_e32 v5, 0xffff0000, v20
	s_waitcnt lgkmcnt(0)
	v_max_f32_e32 v16, v16, v16
	v_lshlrev_b32_e32 v252, 2, v22
	v_fmac_f32_e32 v14, v5, v5
	v_lshlrev_b32_e32 v5, 16, v21
	ds_bpermute_b32 v22, v252, v1
	v_max_f32_e32 v15, v15, v16
	v_fmac_f32_e32 v14, v5, v5
	v_and_b32_e32 v5, 0xffff0000, v21
	ds_bpermute_b32 v16, v252, v15
	v_fmac_f32_e32 v14, v5, v5
	v_add_f32_e32 v3, v3, v14
	v_xor_b32_e32 v14, 4, v250
	v_cmp_lt_i32_e32 vcc, v14, v17
	s_waitcnt lgkmcnt(1)
	v_max_f32_e32 v5, v22, v22
	v_max_f32_e32 v1, v1, v5
	v_cndmask_b32_e32 v14, v250, v14, vcc
	s_waitcnt lgkmcnt(0)
	v_max_f32_e32 v5, v16, v16
	v_lshlrev_b32_e32 v217, 2, v14
	ds_bpermute_b32 v14, v217, v1
	v_max_f32_e32 v5, v15, v5
	ds_bpermute_b32 v15, v217, v5
	v_mov_b32_e32 v16, v0
	s_nop 1
	v_permlane32_swap_b32_e32 v0, v16
	s_waitcnt lgkmcnt(1)
	v_max_f32_e32 v14, v14, v14
	v_max_f32_e32 v1, v1, v14
	s_waitcnt lgkmcnt(0)
	v_max_f32_e32 v14, v15, v15
	v_max_f32_e32 v5, v5, v14
	v_xor_b32_e32 v14, 2, v250
	v_cmp_lt_i32_e32 vcc, v14, v17
	v_add_f32_e32 v0, v0, v16
	ds_write_b128 v230, v[18:21] offset:4096
	v_cndmask_b32_e32 v14, v250, v14, vcc
	v_lshlrev_b32_e32 v223, 2, v14
	ds_bpermute_b32 v14, v223, v1
	ds_bpermute_b32 v15, v223, v5
	v_mov_b32_e32 v18, v3
	s_nop 1
	v_permlane32_swap_b32_e32 v3, v18
	s_waitcnt lgkmcnt(1)
	v_max_f32_e32 v14, v14, v14
	v_max_f32_e32 v1, v1, v14
	s_waitcnt lgkmcnt(0)
	v_max_f32_e32 v14, v15, v15
	v_max_f32_e32 v5, v5, v14
	v_xor_b32_e32 v14, 1, v250
	v_cmp_lt_i32_e32 vcc, v14, v17
	v_add_f32_e32 v3, v3, v18
	v_mov_b32_e32 v21, 0x260
	v_cndmask_b32_e32 v14, v250, v14, vcc
	v_lshlrev_b32_e32 v224, 2, v14
	ds_bpermute_b32 v14, v224, v1
	ds_bpermute_b32 v15, v224, v5
	s_waitcnt lgkmcnt(0)
	s_barrier
	v_max_f32_e32 v14, v14, v14
	v_max_f32_e32 v1, v1, v14
	v_mul_f32_e32 v0, v0, v1
	v_mul_f32_e32 v1, 0x4f800000, v0
	v_cmp_gt_f32_e32 vcc, s52, v0
	v_max_f32_e32 v14, v15, v15
	s_nop 0
	v_cndmask_b32_e32 v1, v0, v1, vcc
	v_sqrt_f32_e32 v15, v1
	v_max_f32_e32 v0, v5, v14
	v_mul_f32_e32 v20, v3, v0
	v_mov_b32_e32 v0, 0
	v_add_u32_e32 v3, -1, v15
	v_fma_f32 v5, -v3, v15, v1
	v_cmp_ge_f32_e64 s[40:41], 0, v5
	v_add_u32_e32 v5, 1, v15
	v_fma_f32 v14, -v5, v15, v1
	v_cndmask_b32_e64 v3, v15, v3, s[40:41]
	v_cmp_lt_f32_e64 s[40:41], 0, v14
	v_mov_b32_e32 v22, v0
	v_mov_b32_e32 v23, v0
	v_cndmask_b32_e64 v3, v3, v5, s[40:41]
	v_mul_f32_e32 v5, 0x37800000, v3
	v_cndmask_b32_e32 v3, v3, v5, vcc
	v_mov_b32_e32 v5, v201
	v_cmp_class_f32_e32 vcc, v1, v21
	v_lshlrev_b64 v[4:5], 1, v[4:5]
	v_lshl_add_u64 v[14:15], s[76:77], 0, v[4:5]
	v_cndmask_b32_e32 v1, v3, v1, vcc
	v_add_u32_e32 v3, 0x2000, v232
	v_lshl_add_u64 v[16:17], v[14:15], 0, s[66:67]
	v_readfirstlane_b32 s8, v3
	v_add_u32_e32 v3, 0x1000, v232
	v_lshl_add_u64 v[18:19], v[14:15], 0, s[26:27]
	global_load_lds_dwordx4 v[16:17], off
	s_mov_b32 m0, s8
	v_readfirstlane_b32 s8, v3
	global_load_lds_dwordx4 v[18:19], off
	v_lshl_add_u64 v[16:17], v[14:15], 0, s[18:19]
	s_mov_b32 m0, s8
	v_add_u32_e32 v3, 0x3000, v232
	global_load_lds_dwordx4 v[16:17], off
	s_mov_b64 s[18:19], 0x2c480
	v_readfirstlane_b32 s8, v3
	v_mov_b32_e32 v3, v201
	v_add_u32_e32 v17, 0x4000, v232
	v_lshl_add_u64 v[14:15], v[14:15], 0, s[18:19]
; __device__ __forceinline__ void attn_item(const P& p, int layer, int item, char* lds) {
;     ...
;   const int vb0 = (int)(uintptr_t)(lds + 2 * ATT_KB) + v_rd_base(lane);
;   const int koff = r32 * 128, ksw = (r32 >> 1) & 7;
;   const unsigned k_src = (tid >> 3) * ZC + (((tid & 7) ^ ((tid >> 4) & 7)) << 3);
;   const int v_kl = (tid & 31) >> 2;
;   const unsigned v_src = (v_kl | ((tid >> 7) << 3)) * ZC + ((tid >> 5) & 3) * 32 + (tid & 3) * 8;
;   char* lw = lds + tid * 16;
;   const float lam = ((const float*)(p.ws + OFF_LAM))[layer];
;   const u16* Kg = z + tokb * ZC + C_DAK + h * 128; const u16* Vg = z + tokb * ZC + C_DAV + h * 128;
;   bf16x8 q1[4], q2[2];
;   char* Qp = lds + 2 * STG + 1024 + tid * 16;
; #pragma unroll
;   for (int d0 = 0; d0 < 4; ++d0) q1[d0] = *(const bf16x8*)(z + (tokq + wid * 32 + r32) * ZC + h * 128 + d0 * 16 + hi * 8);
; #pragma unroll
;   for (int d0 = 0; d0 < 2; ++d0) q2[d0] = *(const bf16x8*)(z + (tokq + wid * 32 + r32) * ZC + h * 128 + 64 + d0 * 16 + hi * 8);
;   __syncthreads();
;   float qs1 = 0.f, qs2 = 0.f;
; #pragma unroll
;   for (int d0 = 0; d0 < 4; ++d0) qs1 += sumsq8(q1[d0]);
; #pragma unroll
;   for (int d0 = 0; d0 < 2; ++d0) qs2 += sumsq8(q2[d0]);
; #pragma unroll
;   for (int d0 = 2; d0 < 4; ++d0) { const bf16x8 t = *(const bf16x8*)(z + (tokq + wid * 32 + r32) * ZC + h * 128 + 64 + d0 * 16 + hi * 8);
;     qs2 += sumsq8(t); *(bf16x8*)(Qp + (d0 - 2) * 4096) = t; }
;   { auto rr = __builtin_amdgcn_permlane32_swap(__float_as_uint(qs1), __float_as_uint(qs1), false, false); qs1 = __uint_as_float(rr[0]) + __uint_as_float(rr[1]); }
;   { auto rr = __builtin_amdgcn_permlane32_swap(__float_as_uint(qs2), __float_as_uint(qs2), false, false); qs2 = __uint_as_float(rr[0]) + __uint_as_float(rr[1]); }
;   float mC1, mC2;
;   { const float* kmx = (const float*)(p.ws + OFF_KMX) + (size_t)((b * 4 + h) * 2) * 128;
;     float k1 = fmaxf(kmx[lane], kmx[64 + lane]), k2 = fmaxf(kmx[128 + lane], kmx[192 + lane]);
; #pragma unroll
;     for (int o = 32; o >= 1; o >>= 1) { k1 = fmaxf(k1, __shfl_xor(k1, o)); k2 = fmaxf(k2, __shfl_xor(k2, o)); }
;     mC1 = sqrtf(qs1 * k1) * 1.4426950408889634f; mC2 = sqrtf(qs2 * k2) * 1.4426950408889634f; }
;   float l1 = 0.f, l2 = 0.f;
;   f32x16 o1[4], o2[4];
; #pragma unroll
;   for (int d = 0; d < 4; ++d) { o1[d] = f32x16{}; o2[d] = f32x16{}; }
;     ...
;   __syncthreads();
;   ISSUE_T(0, 0);
	s_mov_b32 m0, s8
	v_lshl_add_u64 v[2:3], v[2:3], 1, s[76:77]
	s_mov_b64 s[18:19], 0x800
	v_readfirstlane_b32 s8, v17
	v_add_u32_e32 v17, 0x5000, v232
	global_load_lds_dwordx4 v[14:15], off
	v_lshl_add_u64 v[14:15], v[2:3], 0, s[18:19]
	s_mov_b32 m0, s8
	s_mov_b64 s[18:19], 0x16800
	v_readfirstlane_b32 s8, v17
	v_add_u32_e32 v17, 0x6000, v232
	global_load_lds_dwordx4 v[14:15], off
	v_lshl_add_u64 v[14:15], v[2:3], 0, s[18:19]
	s_mov_b32 m0, s8
	s_mov_b64 s[18:19], 0x2c800
	v_readfirstlane_b32 s8, v17
	global_load_lds_dwordx4 v[14:15], off
	v_lshl_add_u64 v[14:15], v[2:3], 0, s[18:19]
	s_mov_b32 m0, s8
	s_mov_b64 s[18:19], 0x42800
	global_load_lds_dwordx4 v[14:15], off
	v_add_u32_e32 v14, 0x7000, v232
	v_lshl_add_u64 v[2:3], v[2:3], 0, s[18:19]
	v_readfirstlane_b32 s8, v14
	s_mov_b32 m0, s8
	v_mul_f32_e32 v14, 0x4f800000, v20
	global_load_lds_dwordx4 v[2:3], off
	v_cmp_gt_f32_e32 vcc, s52, v20
	s_movk_i32 s8, 0x118
	v_bfe_u32 v16, v214, 1, 3
	v_cndmask_b32_e32 v14, v20, v14, vcc
	v_sqrt_f32_e32 v15, v14
	v_mul_f32_e32 v233, 0xbfb8aa3b, v1
	v_lshrrev_b32_e32 v1, 3, v8
	v_mov_b32_e32 v8, v0
	v_add_u32_e32 v2, -1, v15
	v_fma_f32 v3, -v2, v15, v14
	v_cmp_ge_f32_e64 s[40:41], 0, v3
	v_add_u32_e32 v3, 1, v15
	v_mov_b32_e32 v17, v0
	v_cndmask_b32_e64 v2, v15, v2, s[40:41]
	v_fma_f32 v15, -v3, v15, v14
	v_cmp_lt_f32_e64 s[40:41], 0, v15
	v_mov_b32_e32 v15, v0
	v_mov_b32_e32 v18, v0
	v_cndmask_b32_e64 v2, v2, v3, s[40:41]
	v_mul_f32_e32 v3, 0x37800000, v2
	v_cndmask_b32_e32 v2, v2, v3, vcc
	v_and_or_b32 v3, v10, s8, v11
	s_cselect_b32 s8, 0, 0
	s_addk_i32 s8, 0x4000
	v_add3_u32 v234, v13, s8, v3
	v_bitop3_b32 v3, v227, v9, 7 bitop3:0x78
	v_lshlrev_b32_e32 v239, 4, v3
	v_bitop3_b32 v3, v227, v16, 2 bitop3:0x36
	s_movk_i32 s8, 0x5800
	v_cmp_class_f32_e32 vcc, v14, v21
	v_lshlrev_b32_e32 v238, 4, v3
	v_bitop3_b32 v3, v227, v16, 4 bitop3:0x36
	v_mul_lo_u32 v1, v1, s8
	v_cndmask_b32_e32 v2, v2, v14, vcc
	v_lshlrev_b32_e32 v237, 4, v3
	v_bitop3_b32 v3, v227, v16, 6 bitop3:0x36
	v_mad_u32_u24 v1, v6, s33, v1
	s_add_u32 s18, s81, s7
	v_lshlrev_b32_e32 v235, 4, v3
	v_mul_f32_e32 v231, 0xbfb8aa3b, v2
	v_or3_b32 v2, v1, v7, v12
	v_mov_b32_e32 v3, v201
	s_addc_u32 s19, s82, s3
	v_lshl_add_u64 v[206:207], v[2:3], 1, s[18:19]
	v_lshl_add_u64 v[208:209], s[18:19], 0, v[4:5]
	s_mov_b64 s[40:41], 0
	v_mov_b32_e32 v1, v0
	v_mov_b32_e32 v2, v0
	v_mov_b32_e32 v3, v0
	v_mov_b32_e32 v4, v0
	v_mov_b32_e32 v5, v0
	v_mov_b32_e32 v6, v0
	v_mov_b32_e32 v7, v0
	v_mov_b32_e32 v9, v0
	v_mov_b32_e32 v10, v0
	v_mov_b32_e32 v11, v0
	v_mov_b32_e32 v12, v0
	v_mov_b32_e32 v13, v0
	v_mov_b32_e32 v14, v0
	v_mov_b32_e32 v16, v0
	v_mov_b32_e32 v19, v0
	v_mov_b32_e32 v20, v0
	v_mov_b32_e32 v21, v0
	v_mov_b32_e32 v24, v0
	v_mov_b32_e32 v25, v0
	v_mov_b32_e32 v26, v0
	v_mov_b32_e32 v27, v0
	v_mov_b32_e32 v28, v0
	v_mov_b32_e32 v29, v0
	v_mov_b32_e32 v30, v0
	v_mov_b32_e32 v31, v0
	v_mov_b32_e32 v32, v0
	v_mov_b32_e32 v33, v0
	v_mov_b32_e32 v34, v0
	v_mov_b32_e32 v35, v0
	v_mov_b32_e32 v36, v0
	v_mov_b32_e32 v37, v0
	v_mov_b32_e32 v38, v0
	v_mov_b32_e32 v39, v0
	v_mov_b32_e32 v40, v0
	v_mov_b32_e32 v41, v0
	v_mov_b32_e32 v42, v0
	v_mov_b32_e32 v43, v0
	v_mov_b32_e32 v44, v0
	v_mov_b32_e32 v45, v0
	v_mov_b32_e32 v46, v0
	v_mov_b32_e32 v47, v0
	v_mov_b32_e32 v48, v0
	v_mov_b32_e32 v49, v0
	v_mov_b32_e32 v50, v0
	v_mov_b32_e32 v51, v0
	v_mov_b32_e32 v52, v0
	v_mov_b32_e32 v53, v0
	v_mov_b32_e32 v54, v0
	v_mov_b32_e32 v55, v0
	v_mov_b32_e32 v56, v0
	v_mov_b32_e32 v57, v0
	v_mov_b32_e32 v58, v0
	v_mov_b32_e32 v59, v0
	v_mov_b32_e32 v60, v0
	v_mov_b32_e32 v61, v0
	v_mov_b32_e32 v62, v0
	v_mov_b32_e32 v63, v0
	v_mov_b32_e32 v64, v0
	v_mov_b32_e32 v65, v0
	v_mov_b32_e32 v66, v0
	v_mov_b32_e32 v67, v0
	v_mov_b32_e32 v68, v0
	v_mov_b32_e32 v69, v0
	v_mov_b32_e32 v70, v0
	v_mov_b32_e32 v71, v0
	v_mov_b32_e32 v72, v0
	v_mov_b32_e32 v73, v0
	v_mov_b32_e32 v74, v0
	v_mov_b32_e32 v75, v0
	v_mov_b32_e32 v76, v0
	v_mov_b32_e32 v77, v0
	v_mov_b32_e32 v78, v0
	v_mov_b32_e32 v79, v0
	v_mov_b32_e32 v80, v0
	v_mov_b32_e32 v81, v0
	v_mov_b32_e32 v82, v0
	v_mov_b32_e32 v83, v0
	v_mov_b32_e32 v84, v0
	v_mov_b32_e32 v85, v0
	v_mov_b32_e32 v86, v0
	v_mov_b32_e32 v87, v0
	v_mov_b32_e32 v88, v0
	v_mov_b32_e32 v89, v0
	v_mov_b32_e32 v90, v0
	v_mov_b32_e32 v91, v0
	v_mov_b32_e32 v92, v0
	v_mov_b32_e32 v93, v0
	v_mov_b32_e32 v94, v0
	v_mov_b32_e32 v95, v0
	v_mov_b32_e32 v96, v0
	v_mov_b32_e32 v97, v0
	v_mov_b32_e32 v98, v0
	v_mov_b32_e32 v99, v0
	v_mov_b32_e32 v100, v0
	v_mov_b32_e32 v101, v0
	v_mov_b32_e32 v102, v0
	v_mov_b32_e32 v103, v0
	v_mov_b32_e32 v104, v0
	v_mov_b32_e32 v105, v0
	v_mov_b32_e32 v106, v0
	v_mov_b32_e32 v107, v0
	v_mov_b32_e32 v108, v0
	v_mov_b32_e32 v109, v0
	v_mov_b32_e32 v110, v0
	v_mov_b32_e32 v111, v0
	v_mov_b32_e32 v112, v0
	v_mov_b32_e32 v113, v0
	v_mov_b32_e32 v114, v0
	v_mov_b32_e32 v115, v0
	v_mov_b32_e32 v116, v0
	v_mov_b32_e32 v117, v0
	v_mov_b32_e32 v118, v0
	v_mov_b32_e32 v119, v0
	v_mov_b32_e32 v120, v0
	v_mov_b32_e32 v121, v0
	v_mov_b32_e32 v122, v0
	v_mov_b32_e32 v123, v0
	v_mov_b32_e32 v124, v0
	v_mov_b32_e32 v125, v0
	v_mov_b32_e32 v126, v0
	v_mov_b32_e32 v127, v0
	v_mov_b32_e32 v204, v0
	v_mov_b32_e32 v205, v0
	v_add_u32_e32 v239, v236, v239
	v_add_u32_e32 v238, v236, v238
	v_add_u32_e32 v237, v236, v237
	v_add_u32_e32 v235, v236, v235
	v_readfirstlane_b32 s7, v232
	v_readfirstlane_b32 s40, v208
	v_readfirstlane_b32 s41, v209
	v_readfirstlane_b32 s98, v206
	v_readfirstlane_b32 s99, v207
	s_nop 3
	s_sub_u32 s40, s40, 0x1000
	s_subb_u32 s41, s41, 0
	s_sub_u32 s98, s98, 0x1000
	s_subb_u32 s99, s99, 0
	s_nop 1
	v_subrev_u32_e32 v248, s40, v208
	v_subrev_u32_e32 v249, s98, v206
	s_add_u32 s40, s40, 0xa128300
	s_addc_u32 s41, s41, 0
	s_add_u32 s98, s98, 0xa128700
	s_addc_u32 s99, s99, 0
	s_movk_i32 s6, 64
	s_and_b32 s18, s13, 32
	s_cmp_eq_u32 s18, 0
	s_cbranch_scc1 .Lattn_noprio
	s_setprio 1
; #define MFMA(a, b, c) __builtin_amdgcn_mfma_f32_32x32x16_bf16(a, b, c, 0, 0, 0)
; #define PK4N(PV, BASE, OUT) do { u32x4 w_ = {cvtpk(PV[BASE + 0], PV[BASE + 1]), cvtpk(PV[BASE + 2], PV[BASE + 3]), \
;     cvtpk(PV[BASE + 4], PV[BASE + 5]), cvtpk(PV[BASE + 6], PV[BASE + 7])}; OUT = *reinterpret_cast<bf16x8*>(&w_); } while (0)
; #define MAPSTEP(QKT, MC, L, PA0, PA1, PA2, PA3) do { f32x16 p0, p1; \
;     QKT; \
;     sm_fixed(p0, p1, MC, L, PA0, PA1, PA2, PA3); } while (0)
; __device__ __forceinline__ void att_qkt(f32x16& p0, f32x16& p1, const char* Kb, const bf16x8 (&qr)[4], int koff, int ksw, int hi) {
;   p0 = f32x16{}; p1 = f32x16{};
; #pragma unroll
;   for (int d0 = 0; d0 < 4; ++d0) {
;     const int co = ((d0 * 2 + hi) ^ ksw) << 4;
;     const bf16x8 b0 = *(const bf16x8*)(Kb + koff + co);
;     const bf16x8 b1 = *(const bf16x8*)(Kb + koff + 4096 + co);
;     p0 = MFMA(b0, qr[d0], p0); p1 = MFMA(b1, qr[d0], p1);
;   }
; }
; __device__ __forceinline__ void sm_fixed(f32x16& p0, f32x16& p1, float mC, float& l_reg, bf16x8& pa0, bf16x8& pa1, bf16x8& pa2, bf16x8& pa3) {
;   constexpr float C = 1.4426950408889634f;
; #pragma unroll
;   for (int r = 0; r < 16; ++r) p0[r] = __builtin_amdgcn_exp2f(fmaf(p0[r], C, -mC));
; #pragma unroll
;   for (int r = 0; r < 16; ++r) p1[r] = __builtin_amdgcn_exp2f(fmaf(p1[r], C, -mC));
;   float ps = 0;
; #pragma unroll
;   for (int r = 0; r < 16; ++r) ps += p0[r];
; #pragma unroll
;   for (int r = 0; r < 16; ++r) ps += p1[r];
;   { auto rr = __builtin_amdgcn_permlane32_swap(__float_as_uint(ps), __float_as_uint(ps), false, false);
;     ps = __uint_as_float(rr[0]) + __uint_as_float(rr[1]); }
;   l_reg += ps;
;     ...
;   PK4N(p0, 0, pa0); PK4N(p0, 8, pa1); PK4N(p1, 0, pa2); PK4N(p1, 8, pa3);
;     ...
; }
; __device__ __forceinline__ void attn_item(const P& p, int layer, int item, char* lds) {
;     ...
;   __syncthreads();
;   ISSUE_T(0, 0);
;   for (int j = 0; j < NTILE; ++j) {
;     asm volatile("s_waitcnt vmcnt(0)" ::: "memory"); __syncthreads();
;     if (j + 1 < NTILE) ISSUE_T(j + 1, (j + 1) & 1);
;     const char* S = lds + (j & 1) * STG;
;     const int vb = vb0 + (j & 1) * STG;
;     bf16x8 pa0, pa1, pa2, pa3, pb0, pb1, pb2, pb3;
;     MAPSTEP(att_qkt(p0, p1, S, q1, koff, ksw, hi), mC1, l1, pa0, pa1, pa2, pa3);
.Lattn_noprio:
	s_waitcnt lgkmcnt(0)
	s_waitcnt vmcnt(4)
	s_barrier
	ds_read_b128 v[240:243], v239 offset:0
	ds_read_b128 v[244:247], v238 offset:0
	ds_read_b128 v[218:221], v237 offset:0
	ds_read_b128 v[210:213], v235 offset:0
	s_waitcnt lgkmcnt(3)
	v_mfma_f32_32x32x16_bf16 v[128:143], v[240:243], v[180:183], 0
	ds_read_b128 v[240:243], v239 offset:4096
	s_add_u32 m0, s7, 0x8000
	s_nop 0
	global_load_lds_dwordx4 v248, s[40:41]
	s_waitcnt lgkmcnt(3)
	v_mfma_f32_32x32x16_bf16 v[128:143], v[244:247], v[176:179], v[128:143]
	ds_read_b128 v[244:247], v238 offset:4096
	s_add_u32 m0, s7, 0xa000
	s_add_u32 s18, s40, 0x80
	s_addc_u32 s19, s41, 0
	global_load_lds_dwordx4 v248, s[18:19]
	s_waitcnt lgkmcnt(3)
	v_mfma_f32_32x32x16_bf16 v[128:143], v[218:221], v[172:175], v[128:143]
	ds_read_b128 v[218:221], v237 offset:4096
	s_add_u32 m0, s7, 0x9000
	s_add_u32 s18, s40, 0x2c000
	s_addc_u32 s19, s41, 0
	global_load_lds_dwordx4 v248, s[18:19]
	s_waitcnt lgkmcnt(3)
	v_mfma_f32_32x32x16_bf16 v[128:143], v[210:213], v[168:171], v[128:143]
	ds_read_b128 v[210:213], v235 offset:4096
	s_add_u32 m0, s7, 0xb000
	s_add_u32 s18, s40, 0x2c080
	s_addc_u32 s19, s41, 0
	global_load_lds_dwordx4 v248, s[18:19]
	s_add_u32 s40, s40, 0x58000
	s_addc_u32 s41, s41, 0
	s_waitcnt lgkmcnt(3)
	v_mfma_f32_32x32x16_bf16 v[144:159], v[240:243], v[180:183], 0
	ds_read_b128 v[240:243], v239 offset:8192
	s_nop 1
	v_fmamk_f32 v128, v128, 0x3fb8aa3b, v233
	v_fmamk_f32 v129, v129, 0x3fb8aa3b, v233
	v_exp_f32_e32 v128, v128
	v_exp_f32_e32 v129, v129
	v_add_f32_e32 v204, v204, v128
	v_add_f32_e32 v204, v204, v129
	v_cvt_pk_bf16_f32 v184, v128, v129
	v_fmamk_f32 v130, v130, 0x3fb8aa3b, v233
	v_fmamk_f32 v131, v131, 0x3fb8aa3b, v233
	v_exp_f32_e32 v130, v130
	v_exp_f32_e32 v131, v131
	v_add_f32_e32 v204, v204, v130
	v_add_f32_e32 v204, v204, v131
	v_cvt_pk_bf16_f32 v185, v130, v131
	s_waitcnt lgkmcnt(3)
	v_mfma_f32_32x32x16_bf16 v[144:159], v[244:247], v[176:179], v[144:159]
	ds_read_b128 v[244:247], v238 offset:8192
	v_fmamk_f32 v132, v132, 0x3fb8aa3b, v233
	v_fmamk_f32 v133, v133, 0x3fb8aa3b, v233
	v_exp_f32_e32 v132, v132
	v_exp_f32_e32 v133, v133
	v_add_f32_e32 v204, v204, v132
	v_add_f32_e32 v204, v204, v133
	v_cvt_pk_bf16_f32 v186, v132, v133
	v_fmamk_f32 v134, v134, 0x3fb8aa3b, v233
	v_fmamk_f32 v135, v135, 0x3fb8aa3b, v233
	v_exp_f32_e32 v134, v134
	v_exp_f32_e32 v135, v135
	v_add_f32_e32 v204, v204, v134
	v_add_f32_e32 v204, v204, v135
	v_cvt_pk_bf16_f32 v187, v134, v135
	s_waitcnt lgkmcnt(3)
	v_mfma_f32_32x32x16_bf16 v[144:159], v[218:221], v[172:175], v[144:159]
	ds_read_b128 v[218:221], v237 offset:8192
	v_fmamk_f32 v136, v136, 0x3fb8aa3b, v233
	v_fmamk_f32 v137, v137, 0x3fb8aa3b, v233
	v_exp_f32_e32 v136, v136
	v_exp_f32_e32 v137, v137
	v_add_f32_e32 v204, v204, v136
	v_add_f32_e32 v204, v204, v137
	v_cvt_pk_bf16_f32 v188, v136, v137
	v_fmamk_f32 v138, v138, 0x3fb8aa3b, v233
	v_fmamk_f32 v139, v139, 0x3fb8aa3b, v233
	v_exp_f32_e32 v138, v138
	v_exp_f32_e32 v139, v139
	v_add_f32_e32 v204, v204, v138
	v_add_f32_e32 v204, v204, v139
	v_cvt_pk_bf16_f32 v189, v138, v139
	s_waitcnt lgkmcnt(3)
	v_mfma_f32_32x32x16_bf16 v[144:159], v[210:213], v[168:171], v[144:159]
	ds_read_b128 v[210:213], v230 offset:0
	v_fmamk_f32 v140, v140, 0x3fb8aa3b, v233
	v_fmamk_f32 v141, v141, 0x3fb8aa3b, v233
	v_exp_f32_e32 v140, v140
	v_exp_f32_e32 v141, v141
	v_add_f32_e32 v204, v204, v140
	v_add_f32_e32 v204, v204, v141
	v_cvt_pk_bf16_f32 v190, v140, v141
	v_fmamk_f32 v142, v142, 0x3fb8aa3b, v233
	v_fmamk_f32 v143, v143, 0x3fb8aa3b, v233
	v_exp_f32_e32 v142, v142
	v_exp_f32_e32 v143, v143
	v_add_f32_e32 v204, v204, v142
	v_add_f32_e32 v204, v204, v143
	v_cvt_pk_bf16_f32 v191, v142, v143

; #define SBAR() __builtin_amdgcn_sched_barrier(0)
; template <int D0> __device__ __forceinline__ void pv_two(f32x16& oa, f32x16& ob, int vb, bf16x8 a0, bf16x8 a1, bf16x8 a2, bf16x8 a3,
;                                                          bf16x8 b0, bf16x8 b1, bf16x8 b2, bf16x8 b3) {
;     ...
;   { const s16x4 l0 = tr_read<v_rd_off(D0, 0, 0)>(vb), h0 = tr_read<v_rd_off(D0, 0, 1)>(vb), l1 = tr_read<v_rd_off(D0, 1, 0)>(vb), h1 = tr_read<v_rd_off(D0, 1, 1)>(vb);
;     asm volatile("s_waitcnt lgkmcnt(0)" ::: "memory"); SBAR();
;     const bf16x8 v0 = PKV(l0, h0), v1 = PKV(l1, h1);
;     oa = MFMA(a0, v0, oa); ob = MFMA(b0, v0, ob); oa = MFMA(a1, v1, oa); ob = MFMA(b1, v1, ob); }
;   { const s16x4 l2 = tr_read<v_rd_off(D0, 2, 0)>(vb), h2 = tr_read<v_rd_off(D0, 2, 1)>(vb), l3 = tr_read<v_rd_off(D0, 3, 0)>(vb), h3 = tr_read<v_rd_off(D0, 3, 1)>(vb);
;     asm volatile("s_waitcnt lgkmcnt(0)" ::: "memory"); SBAR();
;     const bf16x8 v2 = PKV(l2, h2), v3 = PKV(l3, h3);
;     oa = MFMA(a2, v2, oa); ob = MFMA(b2, v2, ob); oa = MFMA(a3, v3, oa); ob = MFMA(b3, v3, ob); }
;     ...
; }
; __device__ __forceinline__ void att_qkt(f32x16& p0, f32x16& p1, const char* Kb, const bf16x8 (&qr)[4], int koff, int ksw, int hi) {
;   p0 = f32x16{}; p1 = f32x16{};
; #pragma unroll
;   for (int d0 = 0; d0 < 4; ++d0) {
;     const int co = ((d0 * 2 + hi) ^ ksw) << 4;
;     const bf16x8 b0 = *(const bf16x8*)(Kb + koff + co);
;     const bf16x8 b1 = *(const bf16x8*)(Kb + koff + 4096 + co);
;     p0 = MFMA(b0, qr[d0], p0); p1 = MFMA(b1, qr[d0], p1);
;   }
; }
; __device__ __forceinline__ void sm_fixed(f32x16& p0, f32x16& p1, float mC, float& l_reg, bf16x8& pa0, bf16x8& pa1, bf16x8& pa2, bf16x8& pa3) {
;   constexpr float C = 1.4426950408889634f;
; #pragma unroll
;   for (int r = 0; r < 16; ++r) p0[r] = __builtin_amdgcn_exp2f(fmaf(p0[r], C, -mC));
; #pragma unroll
;   for (int r = 0; r < 16; ++r) p1[r] = __builtin_amdgcn_exp2f(fmaf(p1[r], C, -mC));
;   float ps = 0;
; #pragma unroll
;   for (int r = 0; r < 16; ++r) ps += p0[r];
; #pragma unroll
;   for (int r = 0; r < 16; ++r) ps += p1[r];
;   { auto rr = __builtin_amdgcn_permlane32_swap(__float_as_uint(ps), __float_as_uint(ps), false, false);
;     ps = __uint_as_float(rr[0]) + __uint_as_float(rr[1]); }
;   l_reg += ps;
; __device__ __forceinline__ void attn_item(const P& p, int layer, int item, char* lds) {
;     ...
;   for (int j = 0; j < NTILE; ++j) {
.Lattn_exit:
	s_waitcnt lgkmcnt(6)
	v_mfma_f32_32x32x16_bf16 v[0:15], v[184:187], v[240:243], v[0:15]
	ds_read_b64_tr_b16 v[240:241], v234 offset:4096
	ds_read_b64_tr_b16 v[242:243], v234 offset:6144
	v_fmamk_f32 v144, v144, 0x3fb8aa3b, v231
	v_fmamk_f32 v145, v145, 0x3fb8aa3b, v231
	v_exp_f32_e32 v144, v144
	v_exp_f32_e32 v145, v145
	v_add_f32_e32 v205, v205, v144
	v_add_f32_e32 v205, v205, v145
	v_cvt_pk_bf16_f32 v192, v144, v145
	s_waitcnt lgkmcnt(6)
	v_mfma_f32_32x32x16_bf16 v[16:31], v[184:187], v[244:247], v[16:31]
	ds_read_b64_tr_b16 v[244:245], v234 offset:4608
	ds_read_b64_tr_b16 v[246:247], v234 offset:6656
	v_fmamk_f32 v146, v146, 0x3fb8aa3b, v231
	v_fmamk_f32 v147, v147, 0x3fb8aa3b, v231
	v_exp_f32_e32 v146, v146
	v_exp_f32_e32 v147, v147
	v_add_f32_e32 v205, v205, v146
	v_add_f32_e32 v205, v205, v147
	v_cvt_pk_bf16_f32 v193, v146, v147
	s_waitcnt lgkmcnt(6)
	v_mfma_f32_32x32x16_bf16 v[32:47], v[184:187], v[218:221], v[32:47]
	ds_read_b64_tr_b16 v[218:219], v234 offset:5120
	ds_read_b64_tr_b16 v[220:221], v234 offset:7168
	v_fmamk_f32 v148, v148, 0x3fb8aa3b, v231
	v_fmamk_f32 v149, v149, 0x3fb8aa3b, v231
	v_exp_f32_e32 v148, v148
	v_exp_f32_e32 v149, v149
	v_add_f32_e32 v205, v205, v148
	v_add_f32_e32 v205, v205, v149
	v_cvt_pk_bf16_f32 v194, v148, v149
	s_waitcnt lgkmcnt(6)
	v_mfma_f32_32x32x16_bf16 v[48:63], v[184:187], v[210:213], v[48:63]
	ds_read_b64_tr_b16 v[210:211], v234 offset:5632
	ds_read_b64_tr_b16 v[212:213], v234 offset:7680
	v_fmamk_f32 v150, v150, 0x3fb8aa3b, v231
	v_fmamk_f32 v151, v151, 0x3fb8aa3b, v231
	v_exp_f32_e32 v150, v150
	v_exp_f32_e32 v151, v151
	v_add_f32_e32 v205, v205, v150
	v_add_f32_e32 v205, v205, v151
	v_cvt_pk_bf16_f32 v195, v150, v151
	s_waitcnt lgkmcnt(6)
	v_mfma_f32_32x32x16_bf16 v[0:15], v[188:191], v[240:243], v[0:15]
	ds_read_b64_tr_b16 v[240:241], v234 offset:8192
	ds_read_b64_tr_b16 v[242:243], v234 offset:10240
	v_fmamk_f32 v152, v152, 0x3fb8aa3b, v231
	v_fmamk_f32 v153, v153, 0x3fb8aa3b, v231
	v_exp_f32_e32 v152, v152
	v_exp_f32_e32 v153, v153
	v_add_f32_e32 v205, v205, v152
	v_add_f32_e32 v205, v205, v153
	v_cvt_pk_bf16_f32 v196, v152, v153
	s_waitcnt lgkmcnt(6)
	v_mfma_f32_32x32x16_bf16 v[16:31], v[188:191], v[244:247], v[16:31]
	ds_read_b64_tr_b16 v[244:245], v234 offset:8704
	ds_read_b64_tr_b16 v[246:247], v234 offset:10752
	v_fmamk_f32 v154, v154, 0x3fb8aa3b, v231
	v_fmamk_f32 v155, v155, 0x3fb8aa3b, v231
	v_exp_f32_e32 v154, v154
	v_exp_f32_e32 v155, v155
	v_add_f32_e32 v205, v205, v154
	v_add_f32_e32 v205, v205, v155
	v_cvt_pk_bf16_f32 v197, v154, v155
	s_waitcnt lgkmcnt(6)
	v_mfma_f32_32x32x16_bf16 v[32:47], v[188:191], v[218:221], v[32:47]
	ds_read_b64_tr_b16 v[218:219], v234 offset:9216
	ds_read_b64_tr_b16 v[220:221], v234 offset:11264
	v_fmamk_f32 v156, v156, 0x3fb8aa3b, v231
	v_fmamk_f32 v157, v157, 0x3fb8aa3b, v231
	v_exp_f32_e32 v156, v156
	v_exp_f32_e32 v157, v157
	v_add_f32_e32 v205, v205, v156
	v_add_f32_e32 v205, v205, v157
	v_cvt_pk_bf16_f32 v198, v156, v157
	s_waitcnt lgkmcnt(6)
	v_mfma_f32_32x32x16_bf16 v[48:63], v[188:191], v[210:213], v[48:63]
	ds_read_b64_tr_b16 v[210:211], v234 offset:9728
	ds_read_b64_tr_b16 v[212:213], v234 offset:11776
	v_fmamk_f32 v158, v158, 0x3fb8aa3b, v231
	v_fmamk_f32 v159, v159, 0x3fb8aa3b, v231
	v_exp_f32_e32 v158, v158
	v_exp_f32_e32 v159, v159
	v_add_f32_e32 v205, v205, v158
	v_add_f32_e32 v205, v205, v159
	v_cvt_pk_bf16_f32 v199, v158, v159
	s_waitcnt lgkmcnt(6)
	v_mfma_f32_32x32x16_bf16 v[0:15], v[192:195], v[240:243], v[0:15]
	ds_read_b64_tr_b16 v[240:241], v234 offset:12288
	ds_read_b64_tr_b16 v[242:243], v234 offset:14336
	s_waitcnt lgkmcnt(6)
	v_mfma_f32_32x32x16_bf16 v[16:31], v[192:195], v[244:247], v[16:31]
	ds_read_b64_tr_b16 v[244:245], v234 offset:12800
	ds_read_b64_tr_b16 v[246:247], v234 offset:14848
	s_waitcnt lgkmcnt(6)
	v_mfma_f32_32x32x16_bf16 v[32:47], v[192:195], v[218:221], v[32:47]
	ds_read_b64_tr_b16 v[218:219], v234 offset:13312
	ds_read_b64_tr_b16 v[220:221], v234 offset:15360
	s_waitcnt lgkmcnt(6)
	v_mfma_f32_32x32x16_bf16 v[48:63], v[192:195], v[210:213], v[48:63]
	ds_read_b64_tr_b16 v[210:211], v234 offset:13824
	ds_read_b64_tr_b16 v[212:213], v234 offset:15872
	s_waitcnt lgkmcnt(6)
	v_mfma_f32_32x32x16_bf16 v[0:15], v[196:199], v[240:243], v[0:15]
	s_waitcnt lgkmcnt(4)
	v_mfma_f32_32x32x16_bf16 v[16:31], v[196:199], v[244:247], v[16:31]
	s_waitcnt lgkmcnt(2)
	v_mfma_f32_32x32x16_bf16 v[32:47], v[196:199], v[218:221], v[32:47]
	s_waitcnt lgkmcnt(0)
	v_mfma_f32_32x32x16_bf16 v[48:63], v[196:199], v[210:213], v[48:63]
	v_sub_u32_e32 v239, v239, v236
	v_sub_u32_e32 v238, v238, v236
	v_sub_u32_e32 v237, v237, v236
	v_sub_u32_e32 v235, v235, v236
	v_mov_b32_e32 v210, v204
	v_mov_b32_e32 v212, v204
	v_mov_b32_e32 v211, v205
	v_mov_b32_e32 v213, v205
	s_nop 1
	v_permlane32_swap_b32_e32 v210, v212
	v_permlane32_swap_b32_e32 v211, v213
	s_nop 1
	v_add_f32_e32 v204, v210, v212
	v_add_f32_e32 v205, v211, v213
	s_setprio 0
	v_add_u32_e32 v198, v236, v239
	s_waitcnt vmcnt(0)
	s_waitcnt vmcnt(0)
	s_barrier
; __device__ __forceinline__ float bf2f(u16 v) { return __uint_as_float(((unsigned)v) << 16); }
; #define MFMA(a, b, c) __builtin_amdgcn_mfma_f32_32x32x16_bf16(a, b, c, 0, 0, 0)
; #define PK4N(PV, BASE, OUT) do { u32x4 w_ = {cvtpk(PV[BASE + 0], PV[BASE + 1]), cvtpk(PV[BASE + 2], PV[BASE + 3]), \
;     cvtpk(PV[BASE + 4], PV[BASE + 5]), cvtpk(PV[BASE + 6], PV[BASE + 7])}; OUT = *reinterpret_cast<bf16x8*>(&w_); } while (0)
; __device__ __forceinline__ void att_qkt(f32x16& p0, f32x16& p1, const char* Kb, const bf16x8 (&qr)[4], int koff, int ksw, int hi) {
;   p0 = f32x16{}; p1 = f32x16{};
; #pragma unroll
;   for (int d0 = 0; d0 < 4; ++d0) {
;     const int co = ((d0 * 2 + hi) ^ ksw) << 4;
;     const bf16x8 b0 = *(const bf16x8*)(Kb + koff + co);
;     const bf16x8 b1 = *(const bf16x8*)(Kb + koff + 4096 + co);
;     p0 = MFMA(b0, qr[d0], p0); p1 = MFMA(b1, qr[d0], p1);
;   }
; }
; __device__ __forceinline__ void sm_fixed(f32x16& p0, f32x16& p1, float mC, float& l_reg, bf16x8& pa0, bf16x8& pa1, bf16x8& pa2, bf16x8& pa3) {
;   constexpr float C = 1.4426950408889634f;
; #pragma unroll
;   for (int r = 0; r < 16; ++r) p0[r] = __builtin_amdgcn_exp2f(fmaf(p0[r], C, -mC));
; #pragma unroll
;   for (int r = 0; r < 16; ++r) p1[r] = __builtin_amdgcn_exp2f(fmaf(p1[r], C, -mC));
;   float ps = 0;
; #pragma unroll
;   for (int r = 0; r < 16; ++r) ps += p0[r];
; #pragma unroll
;   for (int r = 0; r < 16; ++r) ps += p1[r];
;   { auto rr = __builtin_amdgcn_permlane32_swap(__float_as_uint(ps), __float_as_uint(ps), false, false);
;     ps = __uint_as_float(rr[0]) + __uint_as_float(rr[1]); }
;   l_reg += ps;
;     ...
;   PK4N(p0, 0, pa0); PK4N(p0, 8, pa1); PK4N(p1, 0, pa2); PK4N(p1, 8, pa3);
;     ...
; }
; #pragma unroll
;   for (int q = 0; q < 8; ++q) { const float f = bf2f((u16)v[q]); s += f * f; } return s; }
; __device__ __forceinline__ void att_qkt_p(f32x16& p0, f32x16& p1, const char* Kb, const bf16x8 (&qr)[2], const char* Qp, int koff, int ksw, int hi) {
;   p0 = f32x16{}; p1 = f32x16{};
; #pragma unroll
;   for (int d0 = 0; d0 < 4; ++d0) {
;     const int co = ((d0 * 2 + hi) ^ ksw) << 4;
;     const bf16x8 b0 = *(const bf16x8*)(Kb + koff + co);
;     const bf16x8 b1 = *(const bf16x8*)(Kb + koff + 4096 + co);
;     const bf16x8 qd = d0 < 2 ? qr[d0 & 1] : *(const bf16x8*)(Qp + (d0 - 2) * 4096);
;     p0 = MFMA(b0, qd, p0); p1 = MFMA(b1, qd, p1);
;   }
; }
	ds_read_b128 v[128:131], v198 offset:32768
	ds_read_b128 v[132:135], v198 offset:36864
	v_add_u32_e32 v199, v236, v238
	s_waitcnt lgkmcnt(1)
	v_mfma_f32_32x32x16_bf16 v[144:159], v[128:131], v[180:183], 0
	v_add_u32_e32 v206, v236, v237
	ds_read_b128 v[186:189], v199 offset:36864
	v_add_u32_e32 v207, v236, v235
	v_and_b32_e32 v184, 0x3fffffc0, v214
	s_add_i32 s3, 0, 0x10000
	ds_read_b128 v[190:193], v206 offset:36864
	v_lshl_add_u32 v184, v184, 2, s3
	s_waitcnt lgkmcnt(2)
	v_mfma_f32_32x32x16_bf16 v[128:143], v[132:135], v[180:183], 0
	ds_read_b128 v[180:183], v199 offset:32768
	v_add_u32_e32 v185, 0x8000, v234
	ds_read_b128 v[194:197], v207 offset:36864
	s_waitcnt lgkmcnt(1)
	v_mfma_f32_32x32x16_bf16 v[144:159], v[180:183], v[176:179], v[144:159]
	ds_read_b128 v[180:183], v206 offset:32768
	s_waitcnt lgkmcnt(0)
	v_mfma_f32_32x32x16_bf16 v[144:159], v[180:183], v[172:175], v[144:159]
	ds_read_b128 v[180:183], v207 offset:32768
	v_mfma_f32_32x32x16_bf16 v[128:143], v[186:189], v[176:179], v[128:143]
	s_waitcnt lgkmcnt(0)
	v_mfma_f32_32x32x16_bf16 v[144:159], v[180:183], v[168:171], v[144:159]
	v_mfma_f32_32x32x16_bf16 v[128:143], v[190:193], v[172:175], v[128:143]
	s_nop 10
	v_fmamk_f32 v144, v144, 0x3fb8aa3b, v233
	v_fmamk_f32 v145, v145, 0x3fb8aa3b, v233
	v_exp_f32_e32 v144, v144
	v_fmamk_f32 v146, v146, 0x3fb8aa3b, v233
	v_exp_f32_e32 v145, v145
	v_fmamk_f32 v147, v147, 0x3fb8aa3b, v233
	v_exp_f32_e32 v146, v146
	v_fmamk_f32 v148, v148, 0x3fb8aa3b, v233
	v_exp_f32_e32 v147, v147
	v_fmamk_f32 v149, v149, 0x3fb8aa3b, v233
	v_exp_f32_e32 v148, v148
	v_mfma_f32_32x32x16_bf16 v[128:143], v[194:197], v[168:171], v[128:143]
	v_add_f32_e32 v168, 0, v144
	v_fmamk_f32 v150, v150, 0x3fb8aa3b, v233
	v_exp_f32_e32 v149, v149
	v_add_f32_e32 v168, v145, v168
	v_fmamk_f32 v151, v151, 0x3fb8aa3b, v233
	v_exp_f32_e32 v150, v150
	v_add_f32_e32 v168, v146, v168
	v_fmamk_f32 v152, v152, 0x3fb8aa3b, v233
	v_exp_f32_e32 v151, v151
	v_add_f32_e32 v168, v147, v168
	v_exp_f32_e32 v152, v152
	v_fmamk_f32 v153, v153, 0x3fb8aa3b, v233
	v_add_f32_e32 v168, v148, v168
	v_exp_f32_e32 v153, v153
	v_fmamk_f32 v154, v154, 0x3fb8aa3b, v233
	v_add_f32_e32 v168, v149, v168
	v_exp_f32_e32 v154, v154
	v_fmamk_f32 v155, v155, 0x3fb8aa3b, v233
	v_add_f32_e32 v168, v150, v168
	v_exp_f32_e32 v155, v155
	v_fmamk_f32 v156, v156, 0x3fb8aa3b, v233
	v_add_f32_e32 v168, v151, v168
	v_exp_f32_e32 v156, v156
	v_fmamk_f32 v157, v157, 0x3fb8aa3b, v233
	v_add_f32_e32 v168, v152, v168
	v_exp_f32_e32 v157, v157
	v_fmamk_f32 v158, v158, 0x3fb8aa3b, v233
	v_add_f32_e32 v168, v153, v168
	v_exp_f32_e32 v158, v158
	v_fmamk_f32 v159, v159, 0x3fb8aa3b, v233
	v_add_f32_e32 v168, v154, v168
	v_exp_f32_e32 v159, v159
	v_fmamk_f32 v128, v128, 0x3fb8aa3b, v233
	v_add_f32_e32 v168, v155, v168
	v_exp_f32_e32 v128, v128
	v_fmamk_f32 v129, v129, 0x3fb8aa3b, v233
	v_add_f32_e32 v168, v156, v168
	v_exp_f32_e32 v129, v129
	v_fmamk_f32 v130, v130, 0x3fb8aa3b, v233
	v_add_f32_e32 v168, v157, v168
	v_exp_f32_e32 v130, v130
	v_fmamk_f32 v131, v131, 0x3fb8aa3b, v233
	v_add_f32_e32 v168, v158, v168
	v_exp_f32_e32 v131, v131
	v_fmamk_f32 v132, v132, 0x3fb8aa3b, v233
	v_add_f32_e32 v168, v159, v168
	v_exp_f32_e32 v132, v132
	v_fmamk_f32 v133, v133, 0x3fb8aa3b, v233
	v_add_f32_e32 v168, v128, v168
	v_exp_f32_e32 v133, v133
	v_fmamk_f32 v134, v134, 0x3fb8aa3b, v233
	v_add_f32_e32 v168, v129, v168
	v_exp_f32_e32 v134, v134
	v_fmamk_f32 v135, v135, 0x3fb8aa3b, v233
	v_add_f32_e32 v168, v130, v168
	v_exp_f32_e32 v135, v135
	v_fmamk_f32 v136, v136, 0x3fb8aa3b, v233
	v_add_f32_e32 v168, v131, v168
	v_exp_f32_e32 v136, v136
	v_fmamk_f32 v137, v137, 0x3fb8aa3b, v233
	v_add_f32_e32 v168, v132, v168
	v_exp_f32_e32 v137, v137
	v_fmamk_f32 v138, v138, 0x3fb8aa3b, v233
	v_add_f32_e32 v168, v133, v168
	v_exp_f32_e32 v138, v138
	v_fmamk_f32 v139, v139, 0x3fb8aa3b, v233
	v_add_f32_e32 v168, v134, v168
	v_exp_f32_e32 v139, v139
	v_fmamk_f32 v140, v140, 0x3fb8aa3b, v233
	v_add_f32_e32 v168, v135, v168
	v_exp_f32_e32 v140, v140
	v_fmamk_f32 v141, v141, 0x3fb8aa3b, v233
	v_add_f32_e32 v168, v136, v168
	v_exp_f32_e32 v141, v141
	v_fmamk_f32 v142, v142, 0x3fb8aa3b, v233
	v_add_f32_e32 v168, v137, v168
	v_exp_f32_e32 v142, v142
	v_fmac_f32_e32 v233, 0x3fb8aa3b, v143
	v_add_f32_e32 v168, v138, v168
	v_exp_f32_e32 v143, v233
	v_add_f32_e32 v168, v139, v168
	v_add_f32_e32 v168, v140, v168
	v_add_f32_e32 v168, v141, v168
	v_add_f32_e32 v168, v142, v168
	v_add_f32_e32 v186, v143, v168
	v_mov_b32_e32 v187, v186
	s_nop 1
	v_permlane32_swap_b32_e32 v186, v187
	v_cvt_pk_bf16_f32 v176, v144, v145
	v_cvt_pk_bf16_f32 v177, v146, v147
	v_cvt_pk_bf16_f32 v178, v148, v149
	v_cvt_pk_bf16_f32 v179, v150, v151
	v_cvt_pk_bf16_f32 v180, v152, v153
	v_cvt_pk_bf16_f32 v181, v154, v155
	v_cvt_pk_bf16_f32 v182, v156, v157
	v_cvt_pk_bf16_f32 v183, v158, v159
	v_cvt_pk_bf16_f32 v168, v128, v129
	v_cvt_pk_bf16_f32 v169, v130, v131
	v_cvt_pk_bf16_f32 v170, v132, v133
	v_cvt_pk_bf16_f32 v171, v134, v135
	v_cvt_pk_bf16_f32 v172, v136, v137
	v_cvt_pk_bf16_f32 v173, v138, v139
	v_cvt_pk_bf16_f32 v174, v140, v141
	v_cvt_pk_bf16_f32 v175, v142, v143
	ds_read_b128 v[128:131], v198 offset:40960
	ds_read_b128 v[132:135], v198 offset:45056
	s_waitcnt lgkmcnt(1)
	v_mfma_f32_32x32x16_bf16 v[144:159], v[128:131], v[164:167], 0
	s_waitcnt lgkmcnt(0)
	v_mfma_f32_32x32x16_bf16 v[128:143], v[132:135], v[164:167], 0
	ds_read_b128 v[164:167], v199 offset:40960
	ds_read_b128 v[188:191], v199 offset:45056
	s_waitcnt lgkmcnt(0)
	v_mfma_f32_32x32x16_bf16 v[128:143], v[188:191], v[160:163], v[128:143]
	v_mfma_f32_32x32x16_bf16 v[144:159], v[164:167], v[160:163], v[144:159]
	ds_read_b128 v[160:163], v206 offset:40960
	ds_read_b128 v[164:167], v206 offset:45056
	ds_read_b128 v[188:191], v230
	s_waitcnt lgkmcnt(0)
; #define SBAR() __builtin_amdgcn_sched_barrier(0)
; template <int D0> __device__ __forceinline__ void pv_two(f32x16& oa, f32x16& ob, int vb, bf16x8 a0, bf16x8 a1, bf16x8 a2, bf16x8 a3,
;                                                          bf16x8 b0, bf16x8 b1, bf16x8 b2, bf16x8 b3) {
;     ...
;   { const s16x4 l0 = tr_read<v_rd_off(D0, 0, 0)>(vb), h0 = tr_read<v_rd_off(D0, 0, 1)>(vb), l1 = tr_read<v_rd_off(D0, 1, 0)>(vb), h1 = tr_read<v_rd_off(D0, 1, 1)>(vb);
;     asm volatile("s_waitcnt lgkmcnt(0)" ::: "memory"); SBAR();
;     const bf16x8 v0 = PKV(l0, h0), v1 = PKV(l1, h1);
;     oa = MFMA(a0, v0, oa); ob = MFMA(b0, v0, ob); oa = MFMA(a1, v1, oa); ob = MFMA(b1, v1, ob); }
;   { const s16x4 l2 = tr_read<v_rd_off(D0, 2, 0)>(vb), h2 = tr_read<v_rd_off(D0, 2, 1)>(vb), l3 = tr_read<v_rd_off(D0, 3, 0)>(vb), h3 = tr_read<v_rd_off(D0, 3, 1)>(vb);
;     asm volatile("s_waitcnt lgkmcnt(0)" ::: "memory"); SBAR();
;     const bf16x8 v2 = PKV(l2, h2), v3 = PKV(l3, h3);
;     oa = MFMA(a2, v2, oa); ob = MFMA(b2, v2, ob); oa = MFMA(a3, v3, oa); ob = MFMA(b3, v3, ob); }
;     ...
; }
; __device__ __forceinline__ void att_qkt(f32x16& p0, f32x16& p1, const char* Kb, const bf16x8 (&qr)[4], int koff, int ksw, int hi) {
;   p0 = f32x16{}; p1 = f32x16{};
; #pragma unroll
;   for (int d0 = 0; d0 < 4; ++d0) {
;     const int co = ((d0 * 2 + hi) ^ ksw) << 4;
;     const bf16x8 b0 = *(const bf16x8*)(Kb + koff + co);
;     const bf16x8 b1 = *(const bf16x8*)(Kb + koff + 4096 + co);
;     p0 = MFMA(b0, qr[d0], p0); p1 = MFMA(b1, qr[d0], p1);
;   }
; }
; __device__ __forceinline__ void sm_fixed(f32x16& p0, f32x16& p1, float mC, float& l_reg, bf16x8& pa0, bf16x8& pa1, bf16x8& pa2, bf16x8& pa3) {
;   constexpr float C = 1.4426950408889634f;
; #pragma unroll
;   for (int r = 0; r < 16; ++r) p0[r] = __builtin_amdgcn_exp2f(fmaf(p0[r], C, -mC));
; #pragma unroll
;   for (int r = 0; r < 16; ++r) p1[r] = __builtin_amdgcn_exp2f(fmaf(p1[r], C, -mC));
;   float ps = 0;
; #pragma unroll
;   for (int r = 0; r < 16; ++r) ps += p0[r];
; #pragma unroll
;   for (int r = 0; r < 16; ++r) ps += p1[r];
;   { auto rr = __builtin_amdgcn_permlane32_swap(__float_as_uint(ps), __float_as_uint(ps), false, false);
;     ps = __uint_as_float(rr[0]) + __uint_as_float(rr[1]); }
;   l_reg += ps;
;     ...
;   PK4N(p0, 0, pa0); PK4N(p0, 8, pa1); PK4N(p1, 0, pa2); PK4N(p1, 8, pa3);
;     ...
; }
; #pragma unroll
	v_mfma_f32_32x32x16_bf16 v[128:143], v[164:167], v[188:191], v[128:143]
	v_mfma_f32_32x32x16_bf16 v[144:159], v[160:163], v[188:191], v[144:159]
	ds_read_b128 v[160:163], v207 offset:40960
	ds_read_b128 v[164:167], v207 offset:45056
	ds_read_b128 v[188:191], v230 offset:4096
	s_waitcnt lgkmcnt(0)
	v_mfma_f32_32x32x16_bf16 v[128:143], v[164:167], v[188:191], v[128:143]
	v_mfma_f32_32x32x16_bf16 v[144:159], v[160:163], v[188:191], v[144:159]
	s_nop 10
	v_fmamk_f32 v128, v128, 0x3fb8aa3b, v231
	v_exp_f32_e32 v162, v128
	v_fmamk_f32 v128, v129, 0x3fb8aa3b, v231
	v_exp_f32_e32 v163, v128
	v_fmamk_f32 v128, v130, 0x3fb8aa3b, v231
	v_exp_f32_e32 v164, v128
	v_fmamk_f32 v128, v131, 0x3fb8aa3b, v231
	v_exp_f32_e32 v165, v128
	v_fmamk_f32 v128, v132, 0x3fb8aa3b, v231
	v_exp_f32_e32 v166, v128
	v_fmamk_f32 v128, v133, 0x3fb8aa3b, v231
	v_exp_f32_e32 v167, v128
	v_fmamk_f32 v128, v134, 0x3fb8aa3b, v231
	v_exp_f32_e32 v188, v128
	v_fmamk_f32 v128, v135, 0x3fb8aa3b, v231
	v_exp_f32_e32 v189, v128
	v_fmamk_f32 v128, v136, 0x3fb8aa3b, v231
	v_exp_f32_e32 v190, v128
	v_fmamk_f32 v128, v137, 0x3fb8aa3b, v231
	v_fmamk_f32 v144, v144, 0x3fb8aa3b, v231
	v_exp_f32_e32 v191, v128
	v_fmamk_f32 v128, v138, 0x3fb8aa3b, v231
	v_exp_f32_e32 v160, v144
	v_fmamk_f32 v144, v145, 0x3fb8aa3b, v231
	v_exp_f32_e32 v192, v128
	v_fmamk_f32 v128, v139, 0x3fb8aa3b, v231
	v_exp_f32_e32 v145, v144
	v_fmamk_f32 v144, v146, 0x3fb8aa3b, v231
	v_exp_f32_e32 v193, v128
	v_fmamk_f32 v128, v140, 0x3fb8aa3b, v231
	v_exp_f32_e32 v161, v144
	v_fmamk_f32 v144, v147, 0x3fb8aa3b, v231
	v_exp_f32_e32 v194, v128
	v_fmamk_f32 v128, v141, 0x3fb8aa3b, v231
	v_exp_f32_e32 v147, v144
	v_fmamk_f32 v144, v148, 0x3fb8aa3b, v231
	v_exp_f32_e32 v195, v128
	v_fmamk_f32 v128, v142, 0x3fb8aa3b, v231
	v_exp_f32_e32 v148, v144
	v_fmamk_f32 v144, v149, 0x3fb8aa3b, v231
	v_exp_f32_e32 v196, v128
	v_add_f32_e32 v128, 0, v160
	v_exp_f32_e32 v149, v144
	v_fmamk_f32 v144, v150, 0x3fb8aa3b, v231
	v_add_f32_e32 v128, v145, v128
	v_exp_f32_e32 v150, v144
	v_fmamk_f32 v144, v151, 0x3fb8aa3b, v231
	v_add_f32_e32 v128, v161, v128
	v_exp_f32_e32 v151, v144
	v_fmamk_f32 v144, v152, 0x3fb8aa3b, v231
	v_add_f32_e32 v128, v147, v128
	v_exp_f32_e32 v152, v144
	v_fmamk_f32 v144, v153, 0x3fb8aa3b, v231
	v_add_f32_e32 v128, v148, v128
	v_exp_f32_e32 v153, v144
	v_fmamk_f32 v144, v154, 0x3fb8aa3b, v231
	v_add_f32_e32 v128, v149, v128
	v_exp_f32_e32 v154, v144
	v_fmamk_f32 v144, v155, 0x3fb8aa3b, v231
	v_add_f32_e32 v128, v150, v128
	v_exp_f32_e32 v155, v144
	v_fmamk_f32 v144, v156, 0x3fb8aa3b, v231
	v_add_f32_e32 v128, v151, v128
	v_exp_f32_e32 v156, v144
	v_fmamk_f32 v144, v157, 0x3fb8aa3b, v231
	v_add_f32_e32 v128, v152, v128
	v_exp_f32_e32 v157, v144
	v_fmamk_f32 v144, v158, 0x3fb8aa3b, v231
	v_add_f32_e32 v128, v153, v128
	v_exp_f32_e32 v158, v144
	v_fmamk_f32 v144, v159, 0x3fb8aa3b, v231
	v_add_f32_e32 v128, v154, v128
	v_exp_f32_e32 v159, v144
	v_add_f32_e32 v128, v155, v128
	v_add_f32_e32 v128, v156, v128
	v_add_f32_e32 v128, v157, v128
	v_add_f32_e32 v128, v158, v128
	v_add_f32_e32 v128, v159, v128
	v_add_f32_e32 v128, v162, v128
	v_add_f32_e32 v128, v163, v128
	v_add_f32_e32 v128, v164, v128
	v_add_f32_e32 v128, v165, v128
	v_add_f32_e32 v128, v166, v128
	v_add_f32_e32 v128, v167, v128
	v_add_f32_e32 v128, v188, v128
	v_add_f32_e32 v128, v189, v128
	v_add_f32_e32 v128, v190, v128
	v_add_f32_e32 v128, v191, v128
	v_fmac_f32_e32 v231, 0x3fb8aa3b, v143
	v_add_f32_e32 v128, v192, v128
	v_exp_f32_e32 v143, v231
	v_add_f32_e32 v128, v193, v128
	v_add_f32_e32 v128, v194, v128
	v_add_f32_e32 v128, v195, v128
	v_add_f32_e32 v128, v196, v128
	v_add_f32_e32 v144, v143, v128
	v_mov_b32_e32 v146, v144
	s_nop 1
	v_permlane32_swap_b32_e32 v144, v146
	v_cvt_pk_bf16_f32 v128, v160, v145
	v_cvt_pk_bf16_f32 v129, v161, v147
	v_cvt_pk_bf16_f32 v130, v148, v149
	v_cvt_pk_bf16_f32 v131, v150, v151
	v_cvt_pk_bf16_f32 v132, v152, v153
	v_cvt_pk_bf16_f32 v133, v154, v155
	v_cvt_pk_bf16_f32 v134, v156, v157
	v_cvt_pk_bf16_f32 v135, v158, v159
	v_cvt_pk_bf16_f32 v136, v162, v163
	v_cvt_pk_bf16_f32 v137, v164, v165
	v_cvt_pk_bf16_f32 v138, v166, v167
	v_cvt_pk_bf16_f32 v139, v188, v189
	v_cvt_pk_bf16_f32 v140, v190, v191
	v_cvt_pk_bf16_f32 v141, v192, v193
	v_cvt_pk_bf16_f32 v142, v194, v195
	v_cvt_pk_bf16_f32 v143, v196, v143
	ds_read_b64_tr_b16 v[148:149], v185 offset:0
	ds_read_b64_tr_b16 v[150:151], v185 offset:0x800
	ds_read_b64_tr_b16 v[152:153], v185 offset:0x1000
	ds_read_b64_tr_b16 v[154:155], v185 offset:0x1800
	s_waitcnt lgkmcnt(0)
	s_nop 0
	v_mfma_f32_32x32x16_bf16 v[64:79], v[176:179], v[148:151], v[64:79]
	v_mfma_f32_32x32x16_bf16 v[0:15], v[128:131], v[148:151], v[0:15]
	ds_read_b64_tr_b16 v[148:149], v185 offset:0x2000
	ds_read_b64_tr_b16 v[150:151], v185 offset:0x2800
	v_mfma_f32_32x32x16_bf16 v[64:79], v[180:183], v[152:155], v[64:79]
	v_mfma_f32_32x32x16_bf16 v[0:15], v[132:135], v[152:155], v[0:15]
	ds_read_b64_tr_b16 v[152:153], v185 offset:0x3000
	ds_read_b64_tr_b16 v[154:155], v185 offset:0x3800
	s_waitcnt lgkmcnt(0)
; __device__ __forceinline__ int crow(int r, int hi) { return (r & 3) + 8 * (r >> 2) + 4 * hi; }
; #define SBAR() __builtin_amdgcn_sched_barrier(0)
; #define MFMA(a, b, c) __builtin_amdgcn_mfma_f32_32x32x16_bf16(a, b, c, 0, 0, 0)
; template <int D0> __device__ __forceinline__ void pv_two(f32x16& oa, f32x16& ob, int vb, bf16x8 a0, bf16x8 a1, bf16x8 a2, bf16x8 a3,
;                                                          bf16x8 b0, bf16x8 b1, bf16x8 b2, bf16x8 b3) {
;     ...
;   { const s16x4 l0 = tr_read<v_rd_off(D0, 0, 0)>(vb), h0 = tr_read<v_rd_off(D0, 0, 1)>(vb), l1 = tr_read<v_rd_off(D0, 1, 0)>(vb), h1 = tr_read<v_rd_off(D0, 1, 1)>(vb);
;     asm volatile("s_waitcnt lgkmcnt(0)" ::: "memory"); SBAR();
;     const bf16x8 v0 = PKV(l0, h0), v1 = PKV(l1, h1);
;     oa = MFMA(a0, v0, oa); ob = MFMA(b0, v0, ob); oa = MFMA(a1, v1, oa); ob = MFMA(b1, v1, ob); }
;   { const s16x4 l2 = tr_read<v_rd_off(D0, 2, 0)>(vb), h2 = tr_read<v_rd_off(D0, 2, 1)>(vb), l3 = tr_read<v_rd_off(D0, 3, 0)>(vb), h3 = tr_read<v_rd_off(D0, 3, 1)>(vb);
;     asm volatile("s_waitcnt lgkmcnt(0)" ::: "memory"); SBAR();
;     const bf16x8 v2 = PKV(l2, h2), v3 = PKV(l3, h3);
;     oa = MFMA(a2, v2, oa); ob = MFMA(b2, v2, ob); oa = MFMA(a3, v3, oa); ob = MFMA(b3, v3, ob); }
;     ...
; }
; __device__ __forceinline__ void attn_item(const P& p, int layer, int item, char* lds) {
;     ...
;   float r1[16], r2[16];
;   if (hi == 0) li_l[r32] = l1;
;   asm volatile("s_waitcnt lgkmcnt(0)" ::: "memory");
; #pragma unroll
;   for (int r = 0; r < 16; ++r) r1[r] = 1.f / li_l[crow(r, hi)];
;   asm volatile("s_waitcnt lgkmcnt(0)" ::: "memory");
;   if (hi == 0) li_l[r32] = l2;
;   asm volatile("s_waitcnt lgkmcnt(0)" ::: "memory");
; #pragma unroll
;   for (int r = 0; r < 16; ++r) r2[r] = lam / li_l[crow(r, hi)];
	v_mfma_f32_32x32x16_bf16 v[64:79], v[168:171], v[148:151], v[64:79]
	v_mfma_f32_32x32x16_bf16 v[0:15], v[136:139], v[148:151], v[0:15]
	ds_read_b64_tr_b16 v[148:149], v185 offset:0x200
	ds_read_b64_tr_b16 v[150:151], v185 offset:0xa00
	v_mfma_f32_32x32x16_bf16 v[64:79], v[172:175], v[152:155], v[64:79]
	v_mfma_f32_32x32x16_bf16 v[0:15], v[140:143], v[152:155], v[0:15]
	ds_read_b64_tr_b16 v[152:153], v185 offset:0x1200
	ds_read_b64_tr_b16 v[154:155], v185 offset:0x1a00
	s_waitcnt lgkmcnt(0)
	v_mfma_f32_32x32x16_bf16 v[80:95], v[176:179], v[148:151], v[80:95]
	v_mfma_f32_32x32x16_bf16 v[16:31], v[128:131], v[148:151], v[16:31]
	ds_read_b64_tr_b16 v[148:149], v185 offset:0x2200
	ds_read_b64_tr_b16 v[150:151], v185 offset:0x2a00
	v_mfma_f32_32x32x16_bf16 v[80:95], v[180:183], v[152:155], v[80:95]
	v_mfma_f32_32x32x16_bf16 v[16:31], v[132:135], v[152:155], v[16:31]
	ds_read_b64_tr_b16 v[152:153], v185 offset:0x3200
	ds_read_b64_tr_b16 v[154:155], v185 offset:0x3a00
	s_waitcnt lgkmcnt(0)
	v_mfma_f32_32x32x16_bf16 v[80:95], v[168:171], v[148:151], v[80:95]
	v_mfma_f32_32x32x16_bf16 v[16:31], v[136:139], v[148:151], v[16:31]
	ds_read_b64_tr_b16 v[148:149], v185 offset:0x400
	ds_read_b64_tr_b16 v[150:151], v185 offset:0xc00
	v_mfma_f32_32x32x16_bf16 v[80:95], v[172:175], v[152:155], v[80:95]
	v_mfma_f32_32x32x16_bf16 v[16:31], v[140:143], v[152:155], v[16:31]
	ds_read_b64_tr_b16 v[152:153], v185 offset:0x1400
	ds_read_b64_tr_b16 v[154:155], v185 offset:0x1c00
	s_waitcnt lgkmcnt(0)
	v_mfma_f32_32x32x16_bf16 v[96:111], v[176:179], v[148:151], v[96:111]
	v_mfma_f32_32x32x16_bf16 v[32:47], v[128:131], v[148:151], v[32:47]
	ds_read_b64_tr_b16 v[148:149], v185 offset:0x2400
	ds_read_b64_tr_b16 v[150:151], v185 offset:0x2c00
	v_mfma_f32_32x32x16_bf16 v[96:111], v[180:183], v[152:155], v[96:111]
	v_mfma_f32_32x32x16_bf16 v[32:47], v[132:135], v[152:155], v[32:47]
	ds_read_b64_tr_b16 v[152:153], v185 offset:0x3400
	ds_read_b64_tr_b16 v[154:155], v185 offset:0x3c00
	s_waitcnt lgkmcnt(0)
	v_mfma_f32_32x32x16_bf16 v[96:111], v[168:171], v[148:151], v[96:111]
	v_mfma_f32_32x32x16_bf16 v[32:47], v[136:139], v[148:151], v[32:47]
	ds_read_b64_tr_b16 v[148:149], v185 offset:0x600
	ds_read_b64_tr_b16 v[150:151], v185 offset:0xe00
	v_mfma_f32_32x32x16_bf16 v[96:111], v[172:175], v[152:155], v[96:111]
	v_mfma_f32_32x32x16_bf16 v[32:47], v[140:143], v[152:155], v[32:47]
	ds_read_b64_tr_b16 v[152:153], v185 offset:0x1600
	ds_read_b64_tr_b16 v[154:155], v185 offset:0x1e00
	s_waitcnt lgkmcnt(0)
	v_mfma_f32_32x32x16_bf16 v[112:127], v[176:179], v[148:151], v[112:127]
	v_mfma_f32_32x32x16_bf16 v[48:63], v[128:131], v[148:151], v[48:63]
	ds_read_b64_tr_b16 v[128:129], v185 offset:0x2600
	ds_read_b64_tr_b16 v[130:131], v185 offset:0x2e00
	ds_read_b64_tr_b16 v[148:149], v185 offset:0x3600
	ds_read_b64_tr_b16 v[150:151], v185 offset:0x3e00
	s_waitcnt lgkmcnt(0)
	v_mfma_f32_32x32x16_bf16 v[112:127], v[180:183], v[152:155], v[112:127]
	v_mfma_f32_32x32x16_bf16 v[48:63], v[132:135], v[152:155], v[48:63]
	v_mfma_f32_32x32x16_bf16 v[112:127], v[168:171], v[128:131], v[112:127]
	v_cmp_gt_u32_e32 vcc, 32, v228
	v_lshl_add_u32 v147, v226, 2, v184
	v_mfma_f32_32x32x16_bf16 v[48:63], v[136:139], v[128:131], v[48:63]
	v_mfma_f32_32x32x16_bf16 v[112:127], v[172:175], v[148:151], v[112:127]
	v_mfma_f32_32x32x16_bf16 v[48:63], v[140:143], v[148:151], v[48:63]
	s_and_saveexec_b64 s[6:7], vcc
	v_add_f32_e32 v128, v186, v187
	v_add_f32_e32 v128, v204, v128
	ds_write_b32 v147, v128
	s_or_b64 exec, exec, s[6:7]
	s_waitcnt lgkmcnt(0)
	v_add_u32_e32 v145, v184, v200
	ds_read_b128 v[128:131], v145
	ds_read_b128 v[132:135], v145 offset:32
	ds_read_b128 v[136:139], v145 offset:64
	ds_read_b128 v[140:143], v145 offset:96
	s_waitcnt lgkmcnt(0)
	s_mov_b64 s[6:7], exec
	s_and_b64 s[18:19], s[6:7], vcc
	v_mov_b32_e32 v206, 0x14000
	v_mov_b32_e32 v207, 0x68000
	v_mov_b32_e32 v208, 0x16000
	v_mov_b32_e32 v209, 0x66000
	v_mov_b32_e32 v210, 0x18000
	v_mov_b32_e32 v211, 0x64000
	v_mov_b32_e32 v212, 0x1a000
	v_mov_b32_e32 v213, 0x62000
	v_mov_b32_e32 v214, 0x1c000
	v_mov_b32_e32 v216, 0x60000
	v_mov_b32_e32 v218, 0x1e000
	v_mov_b32_e32 v219, 0x5e000
	v_mov_b32_e32 v220, 0x20000
	v_mov_b32_e32 v221, 0x5c000
	v_mov_b32_e32 v228, 0x22000
	v_mov_b32_e32 v230, 0x5a000
	v_mov_b32_e32 v231, 0x24000
	v_mov_b32_e32 v232, 0x58000
	v_mov_b32_e32 v233, 0x26000
	v_mov_b32_e32 v234, 0x56000
	v_mov_b32_e32 v235, 0x28000
	v_mov_b32_e32 v236, 0x54000
	v_mov_b32_e32 v237, 0x2a000
	v_mov_b32_e32 v238, 0x52000
	v_mov_b32_e32 v239, 0x2c000
	v_mov_b32_e32 v240, 0x50000
	v_mov_b32_e32 v241, 0x2e000
	v_mov_b32_e32 v242, 0x4e000
	v_mov_b32_e32 v243, 0x30000
	v_mov_b32_e32 v244, 0x4c000
	v_mov_b32_e32 v245, 0x32000
	v_mov_b32_e32 v246, 0x4a000
	v_mov_b32_e32 v247, 0x34000
	v_mov_b32_e32 v248, 0x48000
	v_mov_b32_e32 v249, 0x36000
	v_mov_b32_e32 v179, 0x46000
	v_mov_b32_e32 v181, 0x38000
	s_mov_b64 exec, s[18:19]
	s_cbranch_execz .LBB0_270
	v_add_f32_e32 v144, v144, v146
	v_add_f32_e32 v144, v205, v144
	ds_write_b32 v147, v144
	s_branch .LBB0_270
